# MoBA loop: one LDS wait per 4-MFMA group in QK and PV, PV fragment prefetch depth 8 (48 fewer instructions per step and wave)
# baseline (speedup 1.0000x reference)
.LBB0_151:
	s_ashr_i32 s0, s51, 1
	s_sub_i32 s0, s47, s0
	s_lshl_b32 s0, 1, s0
	s_and_b32 s1, s0, s49
	s_cmp_eq_u32 s1, 0
	s_cbranch_scc1 .LBB0_137
	s_mul_i32 s1, s15, 0x11000
	s_add_i32 s1, s1, 0
	v_add_u32_e32 v84, s1, v167
	v_add_u32_e32 v195, v84, v158
	v_add3_u32 v197, s1, v158, v167
	ds_read_b128 v[84:87], v195
	ds_read_b128 v[88:91], v195 offset:64
	ds_read_b128 v[92:95], v195 offset:128
	ds_read_b128 v[96:99], v195 offset:192
	ds_read_b128 v[100:103], v197 offset:4352
	ds_read_b128 v[104:107], v197 offset:4416
	ds_read_b128 v[108:111], v197 offset:4480
	ds_read_b128 v[198:201], v197 offset:4544
	s_waitcnt lgkmcnt(4)
	v_mfma_f32_16x16x32_bf16 v[84:87], v[84:87], v[36:39], 0
	v_mfma_f32_16x16x32_bf16 v[84:87], v[88:91], v[40:43], v[84:87]
	v_mfma_f32_16x16x32_bf16 v[84:87], v[92:95], v[44:47], v[84:87]
	v_mfma_f32_16x16x32_bf16 v[112:115], v[96:99], v[48:51], v[84:87]
	s_nop 5
	ds_read_b128 v[84:87], v197 offset:8704
	ds_read_b128 v[88:91], v197 offset:8768
	ds_read_b128 v[92:95], v197 offset:8832
	ds_read_b128 v[96:99], v197 offset:8896
	s_waitcnt lgkmcnt(4)
	v_mfma_f32_16x16x32_bf16 v[100:103], v[100:103], v[36:39], 0
	v_mfma_f32_16x16x32_bf16 v[100:103], v[104:107], v[40:43], v[100:103]
	v_mfma_f32_16x16x32_bf16 v[100:103], v[108:111], v[44:47], v[100:103]
	v_mfma_f32_16x16x32_bf16 v[108:111], v[198:201], v[48:51], v[100:103]
	s_nop 5
	ds_read_b128 v[100:103], v197 offset:13056
	ds_read_b128 v[198:201], v197 offset:13120
	ds_read_b128 v[202:205], v197 offset:13184
	ds_read_b128 v[206:209], v197 offset:13248
	s_waitcnt lgkmcnt(4)
	v_mfma_f32_16x16x32_bf16 v[84:87], v[84:87], v[36:39], 0
	v_mfma_f32_16x16x32_bf16 v[84:87], v[88:91], v[40:43], v[84:87]
	v_mfma_f32_16x16x32_bf16 v[84:87], v[92:95], v[44:47], v[84:87]
	v_mfma_f32_16x16x32_bf16 v[104:107], v[96:99], v[48:51], v[84:87]
	s_nop 5
	ds_read_b128 v[84:87], v197 offset:17408
	ds_read_b128 v[88:91], v197 offset:17472
	ds_read_b128 v[92:95], v197 offset:17536
	ds_read_b128 v[96:99], v197 offset:17600
	s_waitcnt lgkmcnt(4)
	v_mfma_f32_16x16x32_bf16 v[100:103], v[100:103], v[36:39], 0
	v_mfma_f32_16x16x32_bf16 v[100:103], v[198:201], v[40:43], v[100:103]
	v_mfma_f32_16x16x32_bf16 v[100:103], v[202:205], v[44:47], v[100:103]
	v_mfma_f32_16x16x32_bf16 v[100:103], v[206:209], v[48:51], v[100:103]
	ds_read_b128 v[198:201], v197 offset:21760
	ds_read_b128 v[202:205], v197 offset:21824
	ds_read_b128 v[206:209], v197 offset:21888
	ds_read_b128 v[230:233], v197 offset:21952
	s_waitcnt lgkmcnt(4)
	v_mfma_f32_16x16x32_bf16 v[84:87], v[84:87], v[36:39], 0
	v_mfma_f32_16x16x32_bf16 v[84:87], v[88:91], v[40:43], v[84:87]
	v_mfma_f32_16x16x32_bf16 v[84:87], v[92:95], v[44:47], v[84:87]
	v_mfma_f32_16x16x32_bf16 v[96:99], v[96:99], v[48:51], v[84:87]
	s_nop 5
	ds_read_b128 v[84:87], v197 offset:26112
	ds_read_b128 v[88:91], v197 offset:26176
	ds_read_b128 v[234:237], v197 offset:26240
	ds_read_b128 v[238:241], v197 offset:26304
	s_waitcnt lgkmcnt(4)
	v_mfma_f32_16x16x32_bf16 v[92:95], v[198:201], v[36:39], 0
	v_mfma_f32_16x16x32_bf16 v[92:95], v[202:205], v[40:43], v[92:95]
	v_mfma_f32_16x16x32_bf16 v[92:95], v[206:209], v[44:47], v[92:95]
	v_mfma_f32_16x16x32_bf16 v[92:95], v[230:233], v[48:51], v[92:95]
	ds_read_b128 v[198:201], v197 offset:30464
	ds_read_b128 v[202:205], v197 offset:30528
	ds_read_b128 v[206:209], v197 offset:30592
	ds_read_b128 v[230:233], v197 offset:30656
	s_waitcnt lgkmcnt(4)
	v_mfma_f32_16x16x32_bf16 v[84:87], v[84:87], v[36:39], 0
	v_mfma_f32_16x16x32_bf16 v[84:87], v[88:91], v[40:43], v[84:87]
	v_mfma_f32_16x16x32_bf16 v[84:87], v[234:237], v[44:47], v[84:87]
	v_mfma_f32_16x16x32_bf16 v[88:91], v[238:241], v[48:51], v[84:87]
	s_waitcnt lgkmcnt(0)
	v_mfma_f32_16x16x32_bf16 v[84:87], v[198:201], v[36:39], 0
	v_mfma_f32_16x16x32_bf16 v[84:87], v[202:205], v[40:43], v[84:87]
	v_mfma_f32_16x16x32_bf16 v[84:87], v[206:209], v[44:47], v[84:87]
	v_mfma_f32_16x16x32_bf16 v[84:87], v[230:233], v[48:51], v[84:87]
	ds_read_b128 v[202:205], v195 offset:34816
	ds_read_b128 v[206:209], v195 offset:39168
	ds_read_b128 v[230:233], v195 offset:43520
	ds_read_b128 v[234:237], v195 offset:47872
	v_and_b32_e32 v197, s0, v139
	v_cmp_eq_u32_e64 s[0:1], 0, v197
	s_cmp_lt_u32 s51, 2
	s_mov_b64 s[10:11], -1
	s_cbranch_scc1 .LBB0_154
	v_max3_f32 v197, v112, v113, v114
	v_max3_f32 v198, v96, v97, v98
	v_max3_f32 v197, v197, v115, v108
	v_max3_f32 v198, v198, v99, v92
	v_max3_f32 v197, v197, v109, v110
	v_max3_f32 v198, v198, v93, v94
	v_max3_f32 v197, v197, v111, v104
	v_max3_f32 v198, v198, v95, v88
	v_max3_f32 v197, v197, v105, v106
	v_max3_f32 v198, v198, v89, v90
	v_max3_f32 v197, v197, v107, v100
	v_max3_f32 v198, v198, v91, v84
	v_max3_f32 v197, v197, v101, v102
	v_max3_f32 v198, v198, v85, v86
	v_max_f32_e32 v197, v197, v103
	v_max_f32_e32 v198, v198, v87
	v_max_f32_e32 v197, v197, v198
	v_cndmask_b32_e64 v197, v197, v215, s[0:1]
	s_mov_b64 s[10:11], 0

.LBB0_158:
	s_waitcnt lgkmcnt(0)
	v_add_f32_e32 v198, v198, v199
	v_fmac_f32_e32 v198, v194, v84
	v_cvt_pk_bf16_f32 v112, v112, v113
	v_cvt_pk_bf16_f32 v113, v114, v115
	v_cvt_pk_bf16_f32 v114, v108, v109
	v_cvt_pk_bf16_f32 v115, v110, v111
	v_cvt_pk_bf16_f32 v104, v104, v105
	v_cvt_pk_bf16_f32 v105, v106, v107
	v_cvt_pk_bf16_f32 v106, v100, v101
	v_cvt_pk_bf16_f32 v107, v102, v103
	v_cvt_pk_bf16_f32 v96, v96, v97
	v_cvt_pk_bf16_f32 v97, v98, v99
	v_cvt_pk_bf16_f32 v98, v92, v93
	v_cvt_pk_bf16_f32 v99, v94, v95
	v_cvt_pk_bf16_f32 v88, v88, v89
	v_cvt_pk_bf16_f32 v89, v90, v91
	v_cvt_pk_bf16_f32 v90, v196, v85
	v_cvt_pk_bf16_f32 v91, v86, v87
	ds_read_b128 v[84:87], v195 offset:52224
	ds_read_b128 v[92:95], v195 offset:56576
	ds_read_b128 v[100:103], v195 offset:60928
	ds_read_b128 v[108:111], v195 offset:65280
	s_waitcnt lgkmcnt(4)
	v_mfma_f32_16x16x32_bf16 v[80:83], v[202:205], v[112:115], v[80:83]
	v_mfma_f32_16x16x32_bf16 v[76:79], v[206:209], v[112:115], v[76:79]
	v_mfma_f32_16x16x32_bf16 v[72:75], v[230:233], v[112:115], v[72:75]
	v_mfma_f32_16x16x32_bf16 v[68:71], v[234:237], v[112:115], v[68:71]
	ds_read_b128 v[202:205], v195 offset:34880
	ds_read_b128 v[206:209], v195 offset:39232
	ds_read_b128 v[230:233], v195 offset:43584
	ds_read_b128 v[234:237], v195 offset:47936
	s_waitcnt lgkmcnt(4)
	v_mfma_f32_16x16x32_bf16 v[64:67], v[84:87], v[112:115], v[64:67]
	v_mfma_f32_16x16x32_bf16 v[60:63], v[92:95], v[112:115], v[60:63]
	v_mfma_f32_16x16x32_bf16 v[56:59], v[100:103], v[112:115], v[56:59]
	v_mfma_f32_16x16x32_bf16 v[52:55], v[108:111], v[112:115], v[52:55]
	ds_read_b128 v[84:87], v195 offset:52288
	ds_read_b128 v[92:95], v195 offset:56640
	ds_read_b128 v[100:103], v195 offset:60992
	ds_read_b128 v[108:111], v195 offset:65344
	s_waitcnt lgkmcnt(4)
	v_mfma_f32_16x16x32_bf16 v[80:83], v[202:205], v[104:107], v[80:83]
	v_mfma_f32_16x16x32_bf16 v[76:79], v[206:209], v[104:107], v[76:79]
	v_mfma_f32_16x16x32_bf16 v[72:75], v[230:233], v[104:107], v[72:75]
	v_mfma_f32_16x16x32_bf16 v[68:71], v[234:237], v[104:107], v[68:71]
	ds_read_b128 v[202:205], v195 offset:34944
	ds_read_b128 v[206:209], v195 offset:39296
	ds_read_b128 v[230:233], v195 offset:43648
	ds_read_b128 v[234:237], v195 offset:48000
	s_waitcnt lgkmcnt(4)
	v_mfma_f32_16x16x32_bf16 v[64:67], v[84:87], v[104:107], v[64:67]
	v_mfma_f32_16x16x32_bf16 v[60:63], v[92:95], v[104:107], v[60:63]
	v_mfma_f32_16x16x32_bf16 v[56:59], v[100:103], v[104:107], v[56:59]
	v_mfma_f32_16x16x32_bf16 v[52:55], v[108:111], v[104:107], v[52:55]
	ds_read_b128 v[84:87], v195 offset:52352
	ds_read_b128 v[92:95], v195 offset:56704
	ds_read_b128 v[100:103], v195 offset:61056
	ds_read_b128 v[108:111], v195 offset:65408
	s_waitcnt lgkmcnt(4)
	v_mfma_f32_16x16x32_bf16 v[80:83], v[202:205], v[96:99], v[80:83]
	v_mfma_f32_16x16x32_bf16 v[76:79], v[206:209], v[96:99], v[76:79]
	v_mfma_f32_16x16x32_bf16 v[72:75], v[230:233], v[96:99], v[72:75]
	v_mfma_f32_16x16x32_bf16 v[68:71], v[234:237], v[96:99], v[68:71]
	ds_read_b128 v[202:205], v195 offset:35008
	ds_read_b128 v[206:209], v195 offset:39360
	ds_read_b128 v[230:233], v195 offset:43712
	ds_read_b128 v[234:237], v195 offset:48064
	s_waitcnt lgkmcnt(4)
	v_mfma_f32_16x16x32_bf16 v[64:67], v[84:87], v[96:99], v[64:67]
	v_mfma_f32_16x16x32_bf16 v[60:63], v[92:95], v[96:99], v[60:63]
	v_mfma_f32_16x16x32_bf16 v[56:59], v[100:103], v[96:99], v[56:59]
	v_mfma_f32_16x16x32_bf16 v[52:55], v[108:111], v[96:99], v[52:55]
	ds_read_b128 v[84:87], v195 offset:52416
	ds_read_b128 v[92:95], v195 offset:56768
	ds_read_b128 v[100:103], v195 offset:61120
	ds_read_b128 v[108:111], v195 offset:65472
	s_waitcnt lgkmcnt(4)
	v_mfma_f32_16x16x32_bf16 v[80:83], v[202:205], v[88:91], v[80:83]
	v_mfma_f32_16x16x32_bf16 v[76:79], v[206:209], v[88:91], v[76:79]
	v_mfma_f32_16x16x32_bf16 v[72:75], v[230:233], v[88:91], v[72:75]
	v_mfma_f32_16x16x32_bf16 v[68:71], v[234:237], v[88:91], v[68:71]
	s_waitcnt lgkmcnt(0)
	v_mfma_f32_16x16x32_bf16 v[64:67], v[84:87], v[88:91], v[64:67]
	v_mfma_f32_16x16x32_bf16 v[60:63], v[92:95], v[88:91], v[60:63]
	v_mfma_f32_16x16x32_bf16 v[56:59], v[100:103], v[88:91], v[56:59]
	v_mfma_f32_16x16x32_bf16 v[52:55], v[108:111], v[88:91], v[52:55]
	v_mov_b32_e32 v194, v198
	s_andn2_b64 vcc, exec, s[8:9]
	s_xor_b32 s15, s15, 1
	s_cbranch_vccnz .LBB0_138
	s_branch .LBB0_92
